# differential-attention item table rebuilt only when layer or pass length changes (phase D on even iterations; phase F reuses phase D's table from LDS)
# speedup vs baseline: 1.0108x; 1.0036x over previous
; __device__ __forceinline__ float wave_max(float v) { v = fmaxf(v, xshfl<1>(v)); v = fmaxf(v, xshfl<2>(v)); v = fmaxf(v, xshfl<4>(v)); v = fmaxf(v, xshfl<8>(v)); v = fmaxf(v, xshfl<16>(v)); return half_max(v); }
; #define swa_q_gain INP(8)
; #define swa_k_gain INP(9)
; #define UNIFORM_F(x) __builtin_bit_cast(float, __builtin_amdgcn_readfirstlane(__builtin_bit_cast(int, (float)(x))))
; __global__ void __launch_bounds__(NTHREADS, 2) fwd_kernel(Args args) {
;     ...
;             float bd, bs;
;             const float* dqg = diff_q_gain + l * 64; const float* sqg = swa_q_gain + l * 128;
;             { int ln_ = tid0; asm volatile("" : "+v"(ln_)); const int ln = ln_ & 63; const float* dkg = diff_k_gain + l * 64; const float* skg = swa_k_gain + l * 128;
;               float gq = fabsf(dqg[ln]), gk = fabsf(dkg[ln]);
;               float sq_ = fmaxf(fabsf(sqg[ln]), fabsf(sqg[64 + ln])), sk_ = fmaxf(fabsf(skg[ln]), fabsf(skg[64 + ln]));
;               gq = wave_max(gq); gk = wave_max(gk); sq_ = wave_max(sq_); sk_ = wave_max(sk_);
;               bd = 8.0f * gq * gk * 1.02f; bs = 11.3137085f * sq_ * sk_ * 1.02f; }
;             const bool fixd = (bd * LOG2E < 60.f) && (bd == bd), fixs = (bs * LOG2E < 60.f) && (bs == bs);
;     ...
;             AttnParams PD{dqg, nullptr, diff_lambda + l * 256, diff_norm_gain + l * 128, UNIFORM_F(bd)};
.LBB0_569:
	s_andn2_b64 vcc, exec, s[4:5]
	s_cbranch_vccnz .LBB0_1043
	s_lshr_b32 s85, s35, 8
	s_and_b32 s22, s31, 2
	v_readlane_b32 s4, v254, 26
	s_lshl_b32 s3, s85, s22
	v_readlane_b32 s5, v254, 27
	v_writelane_b32 v254, s3, 34
	s_lshl_b32 s60, s4, 6
	v_readlane_b32 s6, v254, 16
	s_lshl_b32 s4, s4, 7
	s_lshr_b32 s72, s35, 6
	v_readlane_b32 s7, v254, 17
	v_readlane_b32 s14, v251, 0
	s_and_b64 s[6:7], s[6:7], exec
	v_readlane_b32 s15, v251, 1
	s_mov_b64 s[6:7], s[14:15]
	s_load_dwordx2 s[6:7], s[6:7], 0x58
	s_cselect_b32 s3, 6, 4
	v_writelane_b32 v255, s3, 2
	s_add_i32 s3, s3, s22
	s_lshl_b64 s[10:11], s[60:61], 2
	s_mov_b64 s[8:9], s[14:15]
	s_mov_b32 s5, s61
	s_waitcnt lgkmcnt(0)
	s_add_u32 s6, s6, s10
	s_addc_u32 s7, s7, s11
	s_load_dwordx2 s[12:13], s[8:9], 0x40
	s_lshl_b64 s[8:9], s[4:5], 2
	v_mov_b32_e32 v2, v0
	s_mov_b64 s[4:5], s[14:15]
	s_load_dwordx2 s[4:5], s[4:5], 0x60
	s_waitcnt lgkmcnt(0)
	s_add_u32 s12, s12, s8
	s_addc_u32 s13, s13, s9
	v_and_b32_e32 v2, 63, v2
	v_writelane_b32 v254, s3, 62
	s_add_u32 s4, s4, s10
	s_addc_u32 s5, s5, s11
	s_mov_b64 s[10:11], s[14:15]
	v_lshlrev_b32_e32 v2, 2, v2
	global_load_dword v3, v2, s[6:7]
	global_load_dword v8, v2, s[12:13]
	global_load_dword v6, v2, s[4:5]
	v_writelane_b32 v254, s12, 44
	s_load_dwordx2 s[10:11], s[10:11], 0x48
	s_mov_b32 s4, 0x413504f3
	v_writelane_b32 v254, s13, 45
	s_mov_b32 s5, 0x41000000
	s_mov_b32 s3, 0x42700000
	global_load_dword v9, v2, s[12:13] offset:256
	s_waitcnt lgkmcnt(0)
	s_add_u32 s10, s10, s8
	s_addc_u32 s11, s11, s9
	s_mov_b64 s[12:13], s[14:15]
	v_readlane_b32 s16, v251, 4
	v_readlane_b32 s17, v251, 5
	s_waitcnt vmcnt(0)
	v_and_b32_e32 v5, 0x7fffffff, v3
	v_max_f32_e64 v8, |v8|, |v8|
	v_max_f32_e64 v3, |v3|, |v3|
	v_and_b32_e32 v7, 0x7fffffff, v6
	v_max_f32_e64 v9, |v9|, |v9|
	v_max_f32_e32 v8, v8, v9
	global_load_dword v9, v2, s[10:11]
	s_nop 0
	global_load_dword v2, v2, s[10:11] offset:256
	s_mov_b64 s[10:11], s[14:15]
	s_waitcnt vmcnt(1)
	v_max_f32_e64 v9, |v9|, |v9|
	s_waitcnt vmcnt(0)
	v_max_f32_e64 v2, |v2|, |v2|
	v_max_f32_e32 v9, v9, v2
	ds_swizzle_b32 v2, v5 offset:swizzle(SWAP,1)
	v_max_f32_e64 v5, |v6|, |v6|
	s_waitcnt lgkmcnt(0)
	v_max_f32_e32 v2, v2, v2
	v_max_f32_e32 v2, v3, v2
	ds_swizzle_b32 v3, v2 offset:swizzle(SWAP,2)
	s_waitcnt lgkmcnt(0)
	v_max_f32_e32 v3, v3, v3
	v_max_f32_e32 v2, v2, v3
	ds_swizzle_b32 v3, v2 offset:swizzle(SWAP,4)
	s_waitcnt lgkmcnt(0)
	v_max_f32_e32 v3, v3, v3
	v_max_f32_e32 v2, v2, v3
	ds_swizzle_b32 v3, v2 offset:swizzle(SWAP,8)
	s_waitcnt lgkmcnt(0)
	v_max_f32_e32 v3, v3, v3
	v_max_f32_e32 v2, v2, v3
	ds_swizzle_b32 v3, v2 offset:swizzle(SWAP,16)
	s_waitcnt lgkmcnt(0)
	v_max_f32_e32 v3, v3, v3
	v_max_f32_e32 v2, v2, v3
	v_mov_b32_e32 v3, v2
	s_nop 1
	v_permlane32_swap_b32_e32 v2, v3
	v_max_f32_e32 v3, v3, v3
	v_max_f32_e32 v2, v2, v2
	v_max_f32_e32 v3, v2, v3
	ds_swizzle_b32 v2, v7 offset:swizzle(SWAP,1)
	s_waitcnt lgkmcnt(0)
	v_max_f32_e32 v2, v2, v2
	v_max_f32_e32 v2, v5, v2
	ds_swizzle_b32 v5, v2 offset:swizzle(SWAP,2)
	s_waitcnt lgkmcnt(0)
	v_max_f32_e32 v5, v5, v5
	v_max_f32_e32 v2, v2, v5
	ds_swizzle_b32 v5, v2 offset:swizzle(SWAP,4)
	s_waitcnt lgkmcnt(0)
	v_max_f32_e32 v5, v5, v5
	v_max_f32_e32 v2, v2, v5
	ds_swizzle_b32 v5, v2 offset:swizzle(SWAP,8)
	s_waitcnt lgkmcnt(0)
	v_max_f32_e32 v5, v5, v5
	v_max_f32_e32 v2, v2, v5
	ds_swizzle_b32 v5, v2 offset:swizzle(SWAP,16)
	s_waitcnt lgkmcnt(0)
	v_max_f32_e32 v5, v5, v5
	v_max_f32_e32 v2, v2, v5
	v_mov_b32_e32 v5, v2
	s_nop 1
	v_permlane32_swap_b32_e32 v2, v5
	v_max_f32_e32 v5, v5, v5
	v_max_f32_e32 v2, v2, v2
	v_max_f32_e32 v7, v2, v5
	ds_swizzle_b32 v2, v8 offset:swizzle(SWAP,1)
	s_waitcnt lgkmcnt(0)
	v_max_f32_e32 v2, v2, v2
	v_max_f32_e32 v2, v8, v2
	ds_swizzle_b32 v5, v2 offset:swizzle(SWAP,2)
	s_waitcnt lgkmcnt(0)
	v_max_f32_e32 v5, v5, v5
	v_max_f32_e32 v2, v2, v5
	ds_swizzle_b32 v5, v2 offset:swizzle(SWAP,4)
	s_waitcnt lgkmcnt(0)
	v_max_f32_e32 v5, v5, v5
	v_max_f32_e32 v2, v2, v5
	ds_swizzle_b32 v5, v2 offset:swizzle(SWAP,8)
	s_waitcnt lgkmcnt(0)
	v_max_f32_e32 v5, v5, v5
	v_max_f32_e32 v2, v2, v5
	ds_swizzle_b32 v5, v2 offset:swizzle(SWAP,16)
	s_waitcnt lgkmcnt(0)
	v_max_f32_e32 v5, v5, v5
	v_max_f32_e32 v2, v2, v5
	v_mov_b32_e32 v5, v2
	s_nop 1
	v_permlane32_swap_b32_e32 v2, v5
	v_max_f32_e32 v5, v5, v5
	v_max_f32_e32 v2, v2, v2
	v_max_f32_e32 v2, v2, v5
	ds_swizzle_b32 v5, v9 offset:swizzle(SWAP,1)
	v_pk_mul_f32 v[2:3], v[2:3], s[4:5]
	s_mov_b32 s4, 0x3f828f5c
	s_waitcnt lgkmcnt(0)
	v_max_f32_e32 v5, v5, v5
	v_max_f32_e32 v5, v9, v5
	ds_swizzle_b32 v6, v5 offset:swizzle(SWAP,2)
	s_waitcnt lgkmcnt(0)
	v_max_f32_e32 v6, v6, v6
	v_max_f32_e32 v5, v5, v6
	ds_swizzle_b32 v6, v5 offset:swizzle(SWAP,4)
	s_waitcnt lgkmcnt(0)
	v_max_f32_e32 v6, v6, v6
	v_max_f32_e32 v5, v5, v6
	ds_swizzle_b32 v6, v5 offset:swizzle(SWAP,8)
	s_waitcnt lgkmcnt(0)
	v_max_f32_e32 v6, v6, v6
	v_max_f32_e32 v5, v5, v6
	ds_swizzle_b32 v6, v5 offset:swizzle(SWAP,16)
	s_waitcnt lgkmcnt(0)
	v_max_f32_e32 v6, v6, v6
	v_max_f32_e32 v5, v5, v6
	v_mov_b32_e32 v6, v5
	s_load_dwordx2 s[10:11], s[10:11], 0x68
	s_nop 0
	v_permlane32_swap_b32_e32 v5, v6
	v_max_f32_e32 v6, v6, v6
	v_max_f32_e32 v5, v5, v5
	v_max_f32_e32 v6, v5, v6
	s_load_dwordx2 s[12:13], s[12:13], 0x70
	v_pk_mul_f32 v[2:3], v[2:3], v[6:7]
	s_load_dwordx2 s[14:15], s[14:15], 0x50
	v_pk_mul_f32 v[2:3], v[2:3], s[4:5] op_sel_hi:[1,0]
	s_mov_b32 s4, 0x3fb8aa3b
	v_pk_mul_f32 v[6:7], v[2:3], s[4:5] op_sel_hi:[1,0]
	v_cmp_o_f32_e32 vcc, v3, v3
	v_cmp_gt_f32_e64 s[4:5], s3, v6
	v_cmp_gt_f32_e64 s[6:7], s3, v7
	v_readfirstlane_b32 s3, v3
	s_and_b64 s[6:7], vcc, s[6:7]
	s_nop 0
	v_writelane_b32 v255, s3, 6
	s_and_saveexec_b64 s[18:19], s[16:17]
	s_cbranch_execz .LBB0_822
; __device__ __forceinline__ int diff_radius(float bnat, int h) {
;     const float slope_n = exp2f(-(float)(h + 1));
;     const float dn = (2.0f * bnat + logf(2.0f / (1.0f - expf(-slope_n))) + 22.18f) / slope_n;
;     return (dn < 1.0e6f) ? (int)dn + 1 : 1000000;
; }
	s_bitcmp1_b32 s52, 0
	s_cbranch_scc1 .LBB0_822
	s_mov_b32 s16, 0x40b19218
	v_add_f32_e32 v6, v3, v3
	s_mov_b32 s17, 0x40c7b05f
	v_pk_add_f32 v[8:9], v[6:7], s[16:17] op_sel_hi:[0,1]
	s_mov_b32 s30, 0x41b170a4
	v_pk_add_f32 v[8:9], v[8:9], s[30:31] op_sel_hi:[1,0]
	v_readlane_b32 s3, v254, 34
	v_pk_mul_f32 v[8:9], v[8:9], s[48:49]
	s_lshl_b32 s23, s3, 1
	v_cvt_i32_f32_e32 v3, v9
	v_readlane_b32 s3, v253, 40
	v_readlane_b32 s16, v253, 41
	v_readlane_b32 s27, v253, 42
	v_lshl_add_u32 v3, v3, 1, v248
	v_ashrrev_i32_e32 v7, 31, v3
	v_lshrrev_b32_e32 v7, 26, v7
	v_add_u32_e32 v3, v3, v7
	v_mov_b32_e32 v5, s3
	v_ashrrev_i32_e32 v3, 6, v3
	s_mov_b32 s3, 0x49742400
	v_add_u32_e32 v3, 2, v3
	v_cmp_gt_f32_e32 vcc, s3, v9
	s_movk_i32 s26, 0x280
	v_readlane_b32 s38, v254, 9
	v_cndmask_b32_e32 v3, v249, v3, vcc
	v_min_i32_e32 v3, s72, v3
	v_add_u32_e32 v7, 0x7f, v3
	v_ashrrev_i32_e32 v9, 31, v7
	v_lshrrev_b32_e32 v9, 25, v9
	v_add_u32_e32 v7, v7, v9
	v_ashrrev_i32_e32 v7, 7, v7
	v_min_i32_e32 v7, 2, v7
	v_cndmask_b32_e64 v7, 1, v7, s[6:7]
	v_sub_u32_e32 v10, 0, v7
	v_max_i32_e32 v10, v7, v10
	v_cvt_f32_u32_e32 v11, v10
	v_cmp_gt_i32_e32 vcc, 2, v7
	ds_write_b32 v5, v7
	v_mov_b32_e32 v9, s16
	v_cndmask_b32_e64 v5, 0, -1, vcc
	ds_write_b32 v9, v5
	v_rcp_iflag_f32_e32 v9, v11
	v_add3_u32 v3, v3, v7, -1
	v_sub_u32_e32 v11, 0, v3
	v_xor_b32_e32 v7, v3, v7
	v_mul_f32_e32 v9, 0x4f7ffffe, v9
	v_cvt_u32_f32_e32 v9, v9
	v_max_i32_e32 v3, v3, v11
	v_sub_u32_e32 v11, 0, v10
	v_mov_b32_e32 v5, s23
	v_mul_lo_u32 v11, v11, v9
	v_mul_hi_u32 v11, v9, v11
	v_add_u32_e32 v9, v9, v11
	v_mul_hi_u32 v9, v3, v9
	v_mul_lo_u32 v11, v9, v10
	v_sub_u32_e32 v3, v3, v11
	v_cndmask_b32_e64 v5, v5, 0, vcc
	v_add_u32_e32 v11, 1, v9
	v_cmp_ge_u32_e32 vcc, v3, v10
	v_ashrrev_i32_e32 v7, 31, v7
	v_readlane_b32 s16, v253, 43
	v_cndmask_b32_e32 v9, v9, v11, vcc
	v_sub_u32_e32 v11, v3, v10
	v_cndmask_b32_e32 v3, v3, v11, vcc
	v_add_u32_e32 v11, 1, v9
	v_cmp_ge_u32_e32 vcc, v3, v10
	v_readlane_b32 s39, v254, 10
	s_nop 0
	v_cndmask_b32_e32 v3, v9, v11, vcc
	v_cvt_i32_f32_e32 v9, v8
	v_xor_b32_e32 v3, v3, v7
	v_sub_u32_e32 v7, v3, v7
	v_mov_b32_e32 v3, s27
	ds_write_b32 v3, v7
	v_lshl_add_u32 v7, v9, 1, v248
	v_ashrrev_i32_e32 v9, 31, v7
	v_lshrrev_b32_e32 v9, 26, v9
	v_add_u32_e32 v7, v7, v9
	v_ashrrev_i32_e32 v7, 6, v7
	v_add_u32_e32 v7, 2, v7
	v_cmp_gt_f32_e32 vcc, s3, v8
	s_nop 1
	v_cndmask_b32_e32 v7, v249, v7, vcc
	v_min_i32_e32 v7, s72, v7
	v_add_u32_e32 v8, 0x7f, v7
	v_ashrrev_i32_e32 v9, 31, v8
	v_lshrrev_b32_e32 v9, 25, v9
	v_add_u32_e32 v8, v8, v9
	v_ashrrev_i32_e32 v8, 7, v8
	v_add_u32_e32 v9, s23, v5
	v_cndmask_b32_e64 v8, 1, v8, s[6:7]
	v_cmp_lt_u32_e32 vcc, s26, v9
	s_nop 1
	v_cndmask_b32_e64 v10, 2, 1, vcc
	v_cmp_lt_i32_e32 vcc, 1, v8
	s_nop 1
	v_cndmask_b32_e32 v8, v8, v10, vcc
	v_sub_u32_e32 v11, 0, v8
	v_max_i32_e32 v11, v8, v11
	v_cvt_f32_u32_e32 v12, v11
	v_mov_b32_e32 v10, s16
	v_cmp_lt_i32_e32 vcc, 1, v8
	ds_write_b32 v10, v8
	v_readlane_b32 s16, v253, 44
	v_cndmask_b32_e32 v10, -1, v5, vcc
	v_cndmask_b32_e32 v5, v5, v9, vcc
	v_rcp_iflag_f32_e32 v9, v12
	v_mov_b32_e32 v13, s16
	v_add3_u32 v7, v7, v8, -1
	ds_write_b32 v13, v10
	v_mul_f32_e32 v9, 0x4f7ffffe, v9
	v_cvt_u32_f32_e32 v9, v9
	v_sub_u32_e32 v10, 0, v7
	v_xor_b32_e32 v8, v7, v8
	v_max_i32_e32 v7, v7, v10
	v_sub_u32_e32 v10, 0, v11
	v_mul_lo_u32 v10, v10, v9
	v_mul_hi_u32 v10, v9, v10
	v_add_u32_e32 v9, v9, v10
	v_mul_hi_u32 v9, v7, v9
	v_mul_lo_u32 v10, v9, v11
	v_sub_u32_e32 v7, v7, v10
	v_add_u32_e32 v10, 1, v9
	v_cmp_ge_u32_e32 vcc, v7, v11
	v_ashrrev_i32_e32 v8, 31, v8
	v_readlane_b32 s16, v253, 45
	v_cndmask_b32_e32 v9, v9, v10, vcc
	v_sub_u32_e32 v10, v7, v11
	v_cndmask_b32_e32 v7, v7, v10, vcc
	v_add_u32_e32 v10, 1, v9
	v_cmp_ge_u32_e32 vcc, v7, v11
	s_nop 1
	v_cndmask_b32_e32 v7, v9, v10, vcc
	v_xor_b32_e32 v7, v7, v8
	v_sub_u32_e32 v7, v7, v8
	v_mov_b32_e32 v8, s16
	s_mov_b32 s16, 0x4085953b
	s_mov_b32 s17, 0x409b83bc
	ds_write_b32 v8, v7
	v_pk_add_f32 v[8:9], v[6:7], s[16:17] op_sel_hi:[0,1]
	s_mov_b32 s16, 0x42000000
	v_pk_add_f32 v[8:9], v[8:9], s[30:31] op_sel_hi:[1,0]
	s_mov_b32 s17, 0x42800000
	v_pk_mul_f32 v[8:9], v[8:9], s[16:17]
	v_add_u32_e32 v10, s23, v5
	v_cvt_i32_f32_e32 v7, v9
	v_cmp_lt_u32_e32 vcc, s26, v10
	v_readlane_b32 s16, v253, 46
	v_lshl_add_u32 v7, v7, 1, v248
	v_ashrrev_i32_e32 v12, 31, v7
	v_lshrrev_b32_e32 v12, 26, v12
	v_add_u32_e32 v7, v7, v12
	v_ashrrev_i32_e32 v7, 6, v7
	v_cndmask_b32_e64 v11, 2, 1, vcc
	v_add_u32_e32 v7, 2, v7
	v_cmp_gt_f32_e32 vcc, s3, v9
	s_nop 1
	v_cndmask_b32_e32 v7, v249, v7, vcc
	v_min_i32_e32 v7, s72, v7
	v_add_u32_e32 v9, 0x7f, v7
	v_ashrrev_i32_e32 v12, 31, v9
	v_lshrrev_b32_e32 v12, 25, v12
	v_add_u32_e32 v9, v9, v12
	v_ashrrev_i32_e32 v9, 7, v9
	v_cndmask_b32_e64 v9, 1, v9, s[6:7]
	v_cmp_lt_i32_e32 vcc, 1, v9
	s_nop 1
	v_cndmask_b32_e32 v9, v9, v11, vcc
	v_sub_u32_e32 v12, 0, v9
	v_max_i32_e32 v12, v9, v12
	v_cvt_f32_u32_e32 v13, v12
	v_mov_b32_e32 v11, s16
	v_cmp_lt_i32_e32 vcc, 1, v9
	ds_write_b32 v11, v9
	v_readlane_b32 s16, v253, 47
	v_cndmask_b32_e32 v11, -1, v5, vcc
	v_cndmask_b32_e32 v5, v5, v10, vcc
	v_rcp_iflag_f32_e32 v10, v13
	v_mov_b32_e32 v14, s16
	v_add3_u32 v7, v7, v9, -1
	ds_write_b32 v14, v11
	v_mul_f32_e32 v10, 0x4f7ffffe, v10
	v_cvt_u32_f32_e32 v10, v10
	v_sub_u32_e32 v11, 0, v7
	v_xor_b32_e32 v9, v7, v9
	v_max_i32_e32 v7, v7, v11
	v_sub_u32_e32 v11, 0, v12
	v_mul_lo_u32 v11, v11, v10
	v_mul_hi_u32 v11, v10, v11
	v_add_u32_e32 v10, v10, v11
	v_mul_hi_u32 v10, v7, v10
	v_mul_lo_u32 v11, v10, v12
	v_sub_u32_e32 v7, v7, v11
	v_add_u32_e32 v11, 1, v10
	v_cmp_ge_u32_e32 vcc, v7, v12
	v_ashrrev_i32_e32 v9, 31, v9
; __device__ __forceinline__ int diff_radius(float bnat, int h) {
;     const float slope_n = exp2f(-(float)(h + 1));
;     const float dn = (2.0f * bnat + logf(2.0f / (1.0f - expf(-slope_n))) + 22.18f) / slope_n;
;     return (dn < 1.0e6f) ? (int)dn + 1 : 1000000;
; }
	v_readlane_b32 s16, v253, 48
	v_cndmask_b32_e32 v10, v10, v11, vcc
	v_sub_u32_e32 v11, v7, v12
	v_cndmask_b32_e32 v7, v7, v11, vcc
	v_add_u32_e32 v11, 1, v10
	v_cmp_ge_u32_e32 vcc, v7, v12
	s_nop 1
	v_cndmask_b32_e32 v7, v10, v11, vcc
	v_cvt_i32_f32_e32 v10, v8
	v_xor_b32_e32 v7, v7, v9
	v_sub_u32_e32 v7, v7, v9
	v_mov_b32_e32 v9, s16
	ds_write_b32 v9, v7
	v_lshl_add_u32 v7, v10, 1, v248
	v_ashrrev_i32_e32 v9, 31, v7
	v_lshrrev_b32_e32 v9, 26, v9
	v_add_u32_e32 v7, v7, v9
	v_ashrrev_i32_e32 v7, 6, v7
	v_add_u32_e32 v7, 2, v7
	v_cmp_gt_f32_e32 vcc, s3, v8
	v_readlane_b32 s16, v253, 49
	s_nop 0
	v_cndmask_b32_e32 v7, v249, v7, vcc
	v_min_i32_e32 v7, s72, v7
	v_add_u32_e32 v8, 0x7f, v7
	v_ashrrev_i32_e32 v9, 31, v8
	v_lshrrev_b32_e32 v9, 25, v9
	v_add_u32_e32 v8, v8, v9
	v_ashrrev_i32_e32 v8, 7, v8
	v_add_u32_e32 v9, s23, v5
	v_cndmask_b32_e64 v8, 1, v8, s[6:7]
	v_cmp_lt_u32_e32 vcc, s26, v9
	s_nop 1
	v_cndmask_b32_e64 v10, 2, 1, vcc
	v_cmp_lt_i32_e32 vcc, 1, v8
	s_nop 1
	v_cndmask_b32_e32 v8, v8, v10, vcc
	v_sub_u32_e32 v11, 0, v8
	v_max_i32_e32 v11, v8, v11
	v_cvt_f32_u32_e32 v12, v11
	v_mov_b32_e32 v10, s16
	v_cmp_lt_i32_e32 vcc, 1, v8
	ds_write_b32 v10, v8
	v_readlane_b32 s16, v253, 50
	v_cndmask_b32_e32 v10, -1, v5, vcc
	v_cndmask_b32_e32 v5, v5, v9, vcc
	v_rcp_iflag_f32_e32 v9, v12
	v_mov_b32_e32 v13, s16
	v_add3_u32 v7, v7, v8, -1
	ds_write_b32 v13, v10
	v_mul_f32_e32 v9, 0x4f7ffffe, v9
	v_cvt_u32_f32_e32 v9, v9
	v_sub_u32_e32 v10, 0, v7
	v_xor_b32_e32 v8, v7, v8
	v_max_i32_e32 v7, v7, v10
	v_sub_u32_e32 v10, 0, v11
	v_mul_lo_u32 v10, v10, v9
	v_mul_hi_u32 v10, v9, v10
	v_add_u32_e32 v9, v9, v10
	v_mul_hi_u32 v9, v7, v9
	v_mul_lo_u32 v10, v9, v11
	v_sub_u32_e32 v7, v7, v10
	v_add_u32_e32 v10, 1, v9
	v_cmp_ge_u32_e32 vcc, v7, v11
	v_ashrrev_i32_e32 v8, 31, v8
	v_readlane_b32 s16, v253, 51
	v_cndmask_b32_e32 v9, v9, v10, vcc
	v_sub_u32_e32 v10, v7, v11
	v_cndmask_b32_e32 v7, v7, v10, vcc
	v_add_u32_e32 v10, 1, v9
	v_cmp_ge_u32_e32 vcc, v7, v11
	s_nop 1
	v_cndmask_b32_e32 v7, v9, v10, vcc
	v_xor_b32_e32 v7, v7, v8
	v_sub_u32_e32 v7, v7, v8
	v_mov_b32_e32 v8, s16
	s_mov_b32 s16, 0x4035676d
	s_mov_b32 s17, 0x405fcbf4
	ds_write_b32 v8, v7
	v_pk_add_f32 v[8:9], v[6:7], s[16:17] op_sel_hi:[0,1]
	s_mov_b32 s16, 0x413504f3
	s_mov_b32 s17, 0x41000000
	v_pk_add_f32 v[8:9], v[8:9], s[30:31] op_sel_hi:[1,0]
	s_mov_b32 s38, s17
	v_pk_mul_f32 v[8:9], v[8:9], s[38:39]
	v_add_u32_e32 v10, s23, v5
	v_cvt_i32_f32_e32 v7, v9
	v_cmp_lt_u32_e32 vcc, s26, v10
	s_mov_b32 s17, s39
	v_writelane_b32 v254, s16, 9
	v_lshl_add_u32 v7, v7, 1, v248
	v_ashrrev_i32_e32 v12, 31, v7
	v_lshrrev_b32_e32 v12, 26, v12
	v_add_u32_e32 v7, v7, v12
	v_ashrrev_i32_e32 v7, 6, v7
	v_cndmask_b32_e64 v11, 2, 1, vcc
	v_add_u32_e32 v7, 2, v7
	v_cmp_gt_f32_e32 vcc, s3, v9
	v_writelane_b32 v254, s17, 10
	v_readlane_b32 s16, v253, 52
	v_cndmask_b32_e32 v7, v249, v7, vcc
	v_min_i32_e32 v7, s72, v7
	v_add_u32_e32 v9, 0x7f, v7
	v_ashrrev_i32_e32 v12, 31, v9
	v_lshrrev_b32_e32 v12, 25, v12
	v_add_u32_e32 v9, v9, v12
	v_ashrrev_i32_e32 v9, 7, v9
	v_cndmask_b32_e64 v9, 1, v9, s[6:7]
	v_cmp_lt_i32_e32 vcc, 1, v9
	s_nop 1
	v_cndmask_b32_e32 v9, v9, v11, vcc
	v_sub_u32_e32 v12, 0, v9
	v_max_i32_e32 v12, v9, v12
	v_cvt_f32_u32_e32 v13, v12
	v_mov_b32_e32 v11, s16
	v_cmp_lt_i32_e32 vcc, 1, v9
	ds_write_b32 v11, v9
	v_readlane_b32 s16, v253, 53
	v_cndmask_b32_e32 v11, -1, v5, vcc
	v_cndmask_b32_e32 v5, v5, v10, vcc
	v_rcp_iflag_f32_e32 v10, v13
	v_mov_b32_e32 v14, s16
	v_add3_u32 v7, v7, v9, -1
	ds_write_b32 v14, v11
	v_mul_f32_e32 v10, 0x4f7ffffe, v10
	v_cvt_u32_f32_e32 v10, v10
	v_sub_u32_e32 v11, 0, v7
	v_xor_b32_e32 v9, v7, v9
	v_max_i32_e32 v7, v7, v11
	v_sub_u32_e32 v11, 0, v12
	v_mul_lo_u32 v11, v11, v10
	v_mul_hi_u32 v11, v10, v11
	v_add_u32_e32 v10, v10, v11
	v_mul_hi_u32 v10, v7, v10
	v_mul_lo_u32 v11, v10, v12
	v_sub_u32_e32 v7, v7, v11
	v_add_u32_e32 v11, 1, v10
	v_cmp_ge_u32_e32 vcc, v7, v12
	v_ashrrev_i32_e32 v9, 31, v9
	v_readlane_b32 s16, v253, 54
	v_cndmask_b32_e32 v10, v10, v11, vcc
	v_sub_u32_e32 v11, v7, v12
	v_cndmask_b32_e32 v7, v7, v11, vcc
	v_add_u32_e32 v11, 1, v10
	v_cmp_ge_u32_e32 vcc, v7, v12
	s_nop 1
	v_cndmask_b32_e32 v7, v10, v11, vcc
	v_cvt_i32_f32_e32 v10, v8
	v_xor_b32_e32 v7, v7, v9
	v_sub_u32_e32 v7, v7, v9
	v_mov_b32_e32 v9, s16
	ds_write_b32 v9, v7
	v_lshl_add_u32 v7, v10, 1, v248
	v_ashrrev_i32_e32 v9, 31, v7
	v_lshrrev_b32_e32 v9, 26, v9
	v_add_u32_e32 v7, v7, v9
	v_ashrrev_i32_e32 v7, 6, v7
	v_add_u32_e32 v7, 2, v7
	v_cmp_gt_f32_e32 vcc, s3, v8
	v_readlane_b32 s16, v253, 55
	s_nop 0
	v_cndmask_b32_e32 v7, v249, v7, vcc
	v_min_i32_e32 v7, s72, v7
	v_add_u32_e32 v8, 0x7f, v7
	v_ashrrev_i32_e32 v9, 31, v8
	v_lshrrev_b32_e32 v9, 25, v9
	v_add_u32_e32 v8, v8, v9
	v_ashrrev_i32_e32 v8, 7, v8
	v_add_u32_e32 v9, s23, v5
	v_cndmask_b32_e64 v8, 1, v8, s[6:7]
	v_cmp_lt_u32_e32 vcc, s26, v9
	s_nop 1
	v_cndmask_b32_e64 v10, 2, 1, vcc
	v_cmp_lt_i32_e32 vcc, 1, v8
	s_nop 1
	v_cndmask_b32_e32 v8, v8, v10, vcc
	v_sub_u32_e32 v11, 0, v8
	v_max_i32_e32 v11, v8, v11
; __device__ __forceinline__ int diff_radius(float bnat, int h) {
;     const float slope_n = exp2f(-(float)(h + 1));
;     const float dn = (2.0f * bnat + logf(2.0f / (1.0f - expf(-slope_n))) + 22.18f) / slope_n;
;     return (dn < 1.0e6f) ? (int)dn + 1 : 1000000;
; }
	v_cvt_f32_u32_e32 v12, v11
	v_mov_b32_e32 v10, s16
	v_cmp_lt_i32_e32 vcc, 1, v8
	ds_write_b32 v10, v8
	v_readlane_b32 s16, v253, 56
	v_cndmask_b32_e32 v10, -1, v5, vcc
	v_cndmask_b32_e32 v5, v5, v9, vcc
	v_rcp_iflag_f32_e32 v9, v12
	v_mov_b32_e32 v13, s16
	v_add3_u32 v7, v7, v8, -1
	ds_write_b32 v13, v10
	v_mul_f32_e32 v9, 0x4f7ffffe, v9
	v_cvt_u32_f32_e32 v9, v9
	v_sub_u32_e32 v10, 0, v7
	v_xor_b32_e32 v8, v7, v8
	v_max_i32_e32 v7, v7, v10
	v_sub_u32_e32 v10, 0, v11
	v_mul_lo_u32 v10, v10, v9
	v_mul_hi_u32 v10, v9, v10
	v_add_u32_e32 v9, v9, v10
	v_mul_hi_u32 v9, v7, v9
	v_mul_lo_u32 v10, v9, v11
	v_sub_u32_e32 v7, v7, v10
	v_add_u32_e32 v10, 1, v9
	v_cmp_ge_u32_e32 vcc, v7, v11
	v_ashrrev_i32_e32 v8, 31, v8
	v_readlane_b32 s16, v253, 57
	v_cndmask_b32_e32 v9, v9, v10, vcc
	v_sub_u32_e32 v10, v7, v11
	v_cndmask_b32_e32 v7, v7, v10, vcc
	v_add_u32_e32 v10, 1, v9
	v_cmp_ge_u32_e32 vcc, v7, v11
	s_nop 1
	v_cndmask_b32_e32 v7, v9, v10, vcc
	v_xor_b32_e32 v7, v7, v8
	v_sub_u32_e32 v7, v7, v8
	v_mov_b32_e32 v8, s16
	s_mov_b32 s16, 0x3fd01d78
	s_mov_b32 s17, 0x400ceaed
	ds_write_b32 v8, v7
	v_pk_add_f32 v[6:7], v[6:7], s[16:17] op_sel_hi:[0,1]
	s_mov_b32 s16, 2.0
	v_pk_add_f32 v[6:7], v[6:7], s[30:31] op_sel_hi:[1,0]
	s_mov_b32 s17, 4.0
	v_pk_mul_f32 v[6:7], v[6:7], s[16:17]
	v_add_u32_e32 v9, s23, v5
	v_cvt_i32_f32_e32 v8, v7
	v_cmp_lt_u32_e32 vcc, s26, v9
	v_readlane_b32 s16, v253, 58
	v_lshl_add_u32 v8, v8, 1, v248
	v_ashrrev_i32_e32 v11, 31, v8
	v_lshrrev_b32_e32 v11, 26, v11
	v_add_u32_e32 v8, v8, v11
	v_ashrrev_i32_e32 v8, 6, v8
	v_cndmask_b32_e64 v10, 2, 1, vcc
	v_add_u32_e32 v8, 2, v8
	v_cmp_gt_f32_e32 vcc, s3, v7
	s_nop 1
	v_cndmask_b32_e32 v7, v249, v8, vcc
	v_min_i32_e32 v7, s72, v7
	v_add_u32_e32 v8, 0x7f, v7
	v_ashrrev_i32_e32 v11, 31, v8
	v_lshrrev_b32_e32 v11, 25, v11
	v_add_u32_e32 v8, v8, v11
	v_ashrrev_i32_e32 v8, 7, v8
	v_cndmask_b32_e64 v8, 1, v8, s[6:7]
	v_cmp_lt_i32_e32 vcc, 1, v8
	s_nop 1
	v_cndmask_b32_e32 v8, v8, v10, vcc
	v_sub_u32_e32 v11, 0, v8
	v_max_i32_e32 v11, v8, v11
	v_cvt_f32_u32_e32 v12, v11
	v_mov_b32_e32 v10, s16
	v_cmp_lt_i32_e32 vcc, 1, v8
	ds_write_b32 v10, v8
	v_readlane_b32 s16, v253, 59
	v_cndmask_b32_e32 v10, -1, v5, vcc
	v_cndmask_b32_e32 v5, v5, v9, vcc
	v_rcp_iflag_f32_e32 v9, v12
	v_mov_b32_e32 v13, s16
	v_add3_u32 v7, v7, v8, -1
	ds_write_b32 v13, v10
	v_mul_f32_e32 v9, 0x4f7ffffe, v9
	v_cvt_u32_f32_e32 v9, v9
	v_sub_u32_e32 v10, 0, v7
	v_xor_b32_e32 v8, v7, v8
	v_max_i32_e32 v7, v7, v10
	v_sub_u32_e32 v10, 0, v11
	v_mul_lo_u32 v10, v10, v9
	v_mul_hi_u32 v10, v9, v10
	v_add_u32_e32 v9, v9, v10
	v_mul_hi_u32 v9, v7, v9
	v_mul_lo_u32 v10, v9, v11
	v_sub_u32_e32 v7, v7, v10
	v_add_u32_e32 v10, 1, v9
	v_cmp_ge_u32_e32 vcc, v7, v11
	v_ashrrev_i32_e32 v8, 31, v8
	v_readlane_b32 s16, v253, 60
	v_cndmask_b32_e32 v9, v9, v10, vcc
	v_sub_u32_e32 v10, v7, v11
	v_cndmask_b32_e32 v7, v7, v10, vcc
	v_add_u32_e32 v10, 1, v9
	v_cmp_ge_u32_e32 vcc, v7, v11
	s_nop 1
	v_cndmask_b32_e32 v7, v9, v10, vcc
	v_cvt_i32_f32_e32 v9, v6
	v_xor_b32_e32 v7, v7, v8
	v_sub_u32_e32 v7, v7, v8
	v_mov_b32_e32 v8, s16
	ds_write_b32 v8, v7
	v_lshl_add_u32 v7, v9, 1, v248
	v_ashrrev_i32_e32 v8, 31, v7
	v_lshrrev_b32_e32 v8, 26, v8
	v_add_u32_e32 v7, v7, v8
	v_ashrrev_i32_e32 v7, 6, v7
	v_add_u32_e32 v7, 2, v7
	v_cmp_gt_f32_e32 vcc, s3, v6
	v_readlane_b32 s3, v253, 61
	s_nop 0
	v_cndmask_b32_e32 v6, v249, v7, vcc
	v_min_i32_e32 v6, s72, v6
	v_add_u32_e32 v7, 0x7f, v6
	v_ashrrev_i32_e32 v8, 31, v7
	v_lshrrev_b32_e32 v8, 25, v8
	v_add_u32_e32 v7, v7, v8
	v_ashrrev_i32_e32 v7, 7, v7
	v_add_u32_e32 v8, s23, v5
	v_cndmask_b32_e64 v7, 1, v7, s[6:7]
	v_cmp_lt_u32_e32 vcc, s26, v8
	s_mov_b32 s26, -1
	s_nop 0
	v_cndmask_b32_e64 v8, 2, 1, vcc
	v_cmp_lt_i32_e32 vcc, 1, v7
	s_nop 1
	v_cndmask_b32_e32 v7, v7, v8, vcc
	v_mov_b32_e32 v8, s3
	ds_write_b32 v8, v7
	v_sub_u32_e32 v8, 0, v7
	v_max_i32_e32 v8, v7, v8
	v_cvt_f32_u32_e32 v9, v8
	v_cmp_lt_i32_e32 vcc, 1, v7
	v_readlane_b32 s3, v253, 62
	v_add3_u32 v6, v6, v7, -1
	v_cndmask_b32_e32 v5, -1, v5, vcc
	v_mov_b32_e32 v10, s3
	ds_write_b32 v10, v5
	v_rcp_iflag_f32_e32 v5, v9
	v_sub_u32_e32 v9, 0, v6
	v_xor_b32_e32 v7, v6, v7
	v_max_i32_e32 v6, v6, v9
	v_mul_f32_e32 v5, 0x4f7ffffe, v5
	v_cvt_u32_f32_e32 v5, v5
	v_sub_u32_e32 v9, 0, v8
	v_ashrrev_i32_e32 v7, 31, v7
	v_readlane_b32 s3, v253, 63
	v_mul_lo_u32 v9, v9, v5
	v_mul_hi_u32 v9, v5, v9
	v_add_u32_e32 v5, v5, v9
	v_mul_hi_u32 v5, v6, v5
	v_mul_lo_u32 v9, v5, v8
	v_sub_u32_e32 v6, v6, v9
	v_add_u32_e32 v9, 1, v5
	v_cmp_ge_u32_e32 vcc, v6, v8
	s_nop 1
	v_cndmask_b32_e32 v5, v5, v9, vcc
	v_sub_u32_e32 v9, v6, v8
	v_cndmask_b32_e32 v6, v6, v9, vcc
	v_add_u32_e32 v9, 1, v5
	v_cmp_ge_u32_e32 vcc, v6, v8
	v_mov_b32_e32 v6, s3
	s_nop 0
	v_cndmask_b32_e32 v5, v5, v9, vcc
	v_xor_b32_e32 v5, v5, v7
	v_sub_u32_e32 v5, v5, v7
	ds_write_b32 v6, v5
	ds_read_b32 v3, v3
	s_waitcnt lgkmcnt(0)
	v_cmp_lt_i32_e32 vcc, -1, v3
	s_cbranch_vccz .LBB0_573
	v_mov_b32_e32 v3, s27
	ds_read_b32 v3, v3
	s_mov_b32 s26, 7
	s_branch .LBB0_574

; #define DIFF_BOUND(bd_) float bd_; { int ln_ = tid0; asm volatile("" : "+v"(ln_)); const int ln = ln_ & 63; const float* dqg_ = diff_q_gain + l * 64; const float* dkg_ = diff_k_gain + l * 64; \
;         float gq = fabsf(dqg_[ln]), gk = fabsf(dkg_[ln]); \
;         gq = wave_max(gq); gk = wave_max(gk); \
;         bd_ = 8.0f * gq * gk * 1.02f; }
; __global__ void __launch_bounds__(NTHREADS, 2) fwd_kernel(Args args) {
;     ...
;             { DIFF_BOUND(bdf); const bool fixf = (bdf * LOG2E < 60.f) && (bdf == bdf);
;               DIFF_TABLE(bdf, fixf);
.LBB0_1052:
	v_readlane_b32 s4, v254, 26
	v_readlane_b32 s5, v254, 27
	s_lshl_b32 s60, s4, 6
	v_readlane_b32 s4, v254, 16
	v_readlane_b32 s5, v254, 17
	v_readlane_b32 s10, v251, 0
	s_and_b64 s[4:5], s[4:5], exec
	v_readlane_b32 s11, v251, 1
	v_mov_b32_e32 v5, v0
	s_mov_b64 s[4:5], s[10:11]
	s_load_dwordx2 s[4:5], s[4:5], 0x58
	s_load_dwordx2 s[10:11], s[10:11], 0x60
	s_cselect_b32 s38, 6, 4
	s_lshl_b64 s[6:7], s[60:61], 2
	v_and_b32_e32 v5, 63, v5
	s_waitcnt lgkmcnt(0)
	s_add_u32 s4, s4, s6
	s_addc_u32 s5, s5, s7
	v_lshlrev_b32_e32 v5, 2, v5
	global_load_dword v6, v5, s[4:5]
	s_add_u32 s4, s10, s6
	s_addc_u32 s5, s11, s7
	global_load_dword v5, v5, s[4:5]
	s_waitcnt vmcnt(1)
	v_and_b32_e32 v7, 0x7fffffff, v6
	ds_swizzle_b32 v7, v7 offset:swizzle(SWAP,1)
	v_max_f32_e64 v6, |v6|, |v6|
	s_waitcnt vmcnt(0)
	v_and_b32_e32 v8, 0x7fffffff, v5
	ds_swizzle_b32 v8, v8 offset:swizzle(SWAP,1)
	v_max_f32_e64 v5, |v5|, |v5|
	s_waitcnt lgkmcnt(1)
	v_max_f32_e32 v7, v7, v7
	v_max_f32_e32 v6, v6, v7
	ds_swizzle_b32 v7, v6 offset:swizzle(SWAP,2)
	s_waitcnt lgkmcnt(1)
	v_max_f32_e32 v8, v8, v8
	v_max_f32_e32 v5, v5, v8
	ds_swizzle_b32 v8, v5 offset:swizzle(SWAP,2)
	s_waitcnt lgkmcnt(1)
	v_max_f32_e32 v7, v7, v7
	v_max_f32_e32 v6, v6, v7
	ds_swizzle_b32 v7, v6 offset:swizzle(SWAP,4)
	s_waitcnt lgkmcnt(1)
	v_max_f32_e32 v8, v8, v8
	v_max_f32_e32 v5, v5, v8
	ds_swizzle_b32 v8, v5 offset:swizzle(SWAP,4)
	s_waitcnt lgkmcnt(1)
	v_max_f32_e32 v7, v7, v7
	v_max_f32_e32 v6, v6, v7
	ds_swizzle_b32 v7, v6 offset:swizzle(SWAP,8)
	s_waitcnt lgkmcnt(1)
	v_max_f32_e32 v8, v8, v8
	v_max_f32_e32 v5, v5, v8
	ds_swizzle_b32 v8, v5 offset:swizzle(SWAP,8)
	s_waitcnt lgkmcnt(1)
	v_max_f32_e32 v7, v7, v7
	v_max_f32_e32 v6, v6, v7
	ds_swizzle_b32 v7, v6 offset:swizzle(SWAP,16)
	s_waitcnt lgkmcnt(1)
	v_max_f32_e32 v8, v8, v8
	v_max_f32_e32 v8, v5, v8
	ds_swizzle_b32 v9, v8 offset:swizzle(SWAP,16)
	s_waitcnt lgkmcnt(1)
	v_max_f32_e32 v5, v7, v7
	v_max_f32_e32 v5, v6, v5
	v_mov_b32_e32 v6, v5
	s_waitcnt lgkmcnt(0)
	v_max_f32_e32 v7, v9, v9
	v_max_f32_e32 v7, v8, v7
	v_mov_b32_e32 v8, v7
	s_nop 0
	v_permlane32_swap_b32_e32 v5, v6
	v_permlane32_swap_b32_e32 v7, v8
	s_mov_b64 s[10:11], exec
	v_readlane_b32 s4, v251, 4
	v_readlane_b32 s5, v251, 5
	s_and_b64 s[4:5], s[10:11], s[4:5]
	s_mov_b64 exec, s[4:5]
	s_branch .LBB0_1303
	v_max_f32_e32 v5, v5, v5
	v_max_f32_e32 v6, v6, v6
	v_max_f32_e32 v5, v5, v6
	v_max_f32_e32 v6, v7, v7
	v_max_f32_e32 v7, v8, v8
	s_lshr_b32 s4, s35, 8
	s_and_b32 s12, s52, 2
	v_mul_f32_e32 v5, 0x41000000, v5
	v_max_f32_e32 v6, v6, v7
	s_lshl_b32 s4, s4, s12
	v_mul_f32_e32 v5, v5, v6
	s_lshl_b32 s13, s4, 1
	v_mul_f32_e32 v5, 0x3f828f5c, v5
	s_mov_b32 s4, 0x40b19218
	v_add_f32_e32 v6, v5, v5
	s_mov_b32 s5, 0x40c7b05f
	v_pk_add_f32 v[8:9], v[6:7], s[4:5] op_sel_hi:[0,1]
	s_mov_b32 s16, 0x41b170a4
	v_pk_add_f32 v[8:9], v[8:9], s[16:17] op_sel_hi:[1,0]
	v_cmp_o_f32_e32 vcc, v5, v5
	v_pk_mul_f32 v[8:9], v[8:9], s[48:49]
	v_mul_f32_e32 v5, 0x3fb8aa3b, v5
	v_cvt_i32_f32_e32 v7, v9
	s_mov_b32 s4, 0x42700000
	v_cmp_gt_f32_e64 s[4:5], s4, v5
	s_mov_b32 s15, 0x49742400
	v_lshl_add_u32 v5, v7, 1, v248
	v_ashrrev_i32_e32 v7, 31, v5
	v_lshrrev_b32_e32 v7, 26, v7
	v_add_u32_e32 v5, v5, v7
	v_ashrrev_i32_e32 v5, 6, v5
	v_add_u32_e32 v5, 2, v5
	v_cmp_gt_f32_e64 s[6:7], s15, v9
	s_lshr_b32 s14, s35, 6
	s_and_b64 vcc, vcc, s[4:5]
	v_cndmask_b32_e64 v5, v249, v5, s[6:7]
	v_min_i32_e32 v5, s14, v5
	v_add_u32_e32 v7, 0x7f, v5
	v_ashrrev_i32_e32 v9, 31, v7
	v_lshrrev_b32_e32 v9, 25, v9
	v_add_u32_e32 v7, v7, v9
	v_ashrrev_i32_e32 v7, 7, v7
	v_min_i32_e32 v7, 2, v7
	v_cndmask_b32_e32 v7, 1, v7, vcc
	v_sub_u32_e32 v11, 0, v7
	v_max_i32_e32 v11, v7, v11
	v_cvt_f32_u32_e32 v12, v11
	v_readlane_b32 s4, v253, 40
	v_readlane_b32 s6, v253, 41
	v_add3_u32 v5, v5, v7, -1
	v_mov_b32_e32 v9, s4
	v_cmp_gt_i32_e64 s[4:5], 2, v7
	ds_write_b32 v9, v7
	v_mov_b32_e32 v10, s6
	v_cndmask_b32_e64 v9, 0, -1, s[4:5]
	ds_write_b32 v10, v9
	v_rcp_iflag_f32_e32 v10, v12
	v_sub_u32_e32 v12, 0, v5
	v_xor_b32_e32 v7, v5, v7
	v_max_i32_e32 v5, v5, v12
	v_mul_f32_e32 v10, 0x4f7ffffe, v10
	v_cvt_u32_f32_e32 v10, v10
	v_sub_u32_e32 v12, 0, v11
	v_mov_b32_e32 v9, s13
	v_cndmask_b32_e64 v9, v9, 0, s[4:5]
	v_mul_lo_u32 v12, v12, v10
	v_mul_hi_u32 v12, v10, v12
	v_add_u32_e32 v10, v10, v12
	v_mul_hi_u32 v10, v5, v10
	v_mul_lo_u32 v12, v10, v11
	v_sub_u32_e32 v5, v5, v12
	v_add_u32_e32 v12, 1, v10
	v_cmp_ge_u32_e64 s[4:5], v5, v11
	v_ashrrev_i32_e32 v7, 31, v7
	s_movk_i32 s6, 0x280
	v_cndmask_b32_e64 v10, v10, v12, s[4:5]
	v_sub_u32_e32 v12, v5, v11
	v_cndmask_b32_e64 v5, v5, v12, s[4:5]
	v_add_u32_e32 v12, 1, v10
	v_cmp_ge_u32_e64 s[4:5], v5, v11
	v_readlane_b32 s7, v253, 44
	v_readlane_b32 s18, v254, 9
	v_cndmask_b32_e64 v5, v10, v12, s[4:5]
	v_cvt_i32_f32_e32 v10, v8
	v_xor_b32_e32 v5, v5, v7
	v_sub_u32_e32 v7, v5, v7
	v_mov_b32_e32 v5, s72
	ds_write_b32 v5, v7
	v_lshl_add_u32 v7, v10, 1, v248
	v_ashrrev_i32_e32 v10, 31, v7
	v_lshrrev_b32_e32 v10, 26, v10
	v_add_u32_e32 v7, v7, v10
	v_ashrrev_i32_e32 v7, 6, v7
	v_add_u32_e32 v7, 2, v7
	v_cmp_gt_f32_e64 s[4:5], s15, v8
	v_mov_b32_e32 v14, s7
	v_readlane_b32 s7, v253, 47
	v_cndmask_b32_e64 v7, v249, v7, s[4:5]
	v_min_i32_e32 v7, s14, v7
	v_add_u32_e32 v8, 0x7f, v7
	v_ashrrev_i32_e32 v10, 31, v8
	v_lshrrev_b32_e32 v10, 25, v10
	v_add_u32_e32 v8, v8, v10
	v_ashrrev_i32_e32 v8, 7, v8
	v_add_u32_e32 v10, s13, v9
	v_cndmask_b32_e32 v8, 1, v8, vcc
	v_cmp_lt_u32_e64 s[4:5], s6, v10
	v_mov_b32_e32 v15, s7
	v_readlane_b32 s7, v253, 50
	v_cndmask_b32_e64 v11, 2, 1, s[4:5]
	v_cmp_lt_i32_e64 s[4:5], 1, v8
	v_readlane_b32 s19, v254, 10
	s_nop 0
	v_cndmask_b32_e64 v8, v8, v11, s[4:5]
; __device__ __forceinline__ int diff_radius(float bnat, int h) {
;     const float slope_n = exp2f(-(float)(h + 1));
;     const float dn = (2.0f * bnat + logf(2.0f / (1.0f - expf(-slope_n))) + 22.18f) / slope_n;
;     return (dn < 1.0e6f) ? (int)dn + 1 : 1000000;
; }
	v_sub_u32_e32 v12, 0, v8
	v_max_i32_e32 v12, v8, v12
	v_cvt_f32_u32_e32 v13, v12
	v_readlane_b32 s4, v253, 43
	v_add3_u32 v7, v7, v8, -1
	s_nop 0
	v_mov_b32_e32 v11, s4
	v_cmp_lt_i32_e64 s[4:5], 1, v8
	ds_write_b32 v11, v8
	v_xor_b32_e32 v8, v7, v8
	v_cndmask_b32_e64 v11, -1, v9, s[4:5]
	v_cndmask_b32_e64 v10, v9, v10, s[4:5]
	v_rcp_iflag_f32_e32 v9, v13
	ds_write_b32 v14, v11
	v_sub_u32_e32 v11, 0, v7
	v_max_i32_e32 v7, v7, v11
	v_mul_f32_e32 v9, 0x4f7ffffe, v9
	v_cvt_u32_f32_e32 v9, v9
	v_sub_u32_e32 v11, 0, v12
	v_ashrrev_i32_e32 v8, 31, v8
	v_mul_lo_u32 v11, v11, v9
	v_mul_hi_u32 v11, v9, v11
	v_add_u32_e32 v9, v9, v11
	v_mul_hi_u32 v9, v7, v9
	v_mul_lo_u32 v11, v9, v12
	v_sub_u32_e32 v7, v7, v11
	v_add_u32_e32 v11, 1, v9
	v_cmp_ge_u32_e64 s[4:5], v7, v12
	s_nop 1
	v_cndmask_b32_e64 v9, v9, v11, s[4:5]
	v_sub_u32_e32 v11, v7, v12
	v_cndmask_b32_e64 v7, v7, v11, s[4:5]
	v_add_u32_e32 v11, 1, v9
	v_cmp_ge_u32_e64 s[4:5], v7, v12
	s_nop 1
	v_cndmask_b32_e64 v7, v9, v11, s[4:5]
	v_xor_b32_e32 v7, v7, v8
	v_readlane_b32 s4, v253, 45
	v_sub_u32_e32 v7, v7, v8
	v_add_u32_e32 v11, s13, v10
	v_mov_b32_e32 v8, s4
	s_mov_b32 s4, 0x4085953b
	s_mov_b32 s5, 0x409b83bc
	ds_write_b32 v8, v7
	v_pk_add_f32 v[8:9], v[6:7], s[4:5] op_sel_hi:[0,1]
	s_mov_b32 s4, 0x42000000
	v_pk_add_f32 v[8:9], v[8:9], s[16:17] op_sel_hi:[1,0]
	s_mov_b32 s5, 0x42800000
	v_pk_mul_f32 v[8:9], v[8:9], s[4:5]
	v_cmp_lt_u32_e64 s[4:5], s6, v11
	v_cvt_i32_f32_e32 v7, v9
	v_lshl_add_u32 v7, v7, 1, v248
	v_ashrrev_i32_e32 v13, 31, v7
	v_lshrrev_b32_e32 v13, 26, v13
	v_add_u32_e32 v7, v7, v13
	v_ashrrev_i32_e32 v7, 6, v7
	v_cndmask_b32_e64 v12, 2, 1, s[4:5]
	v_add_u32_e32 v7, 2, v7
	v_cmp_gt_f32_e64 s[4:5], s15, v9
	s_nop 1
	v_cndmask_b32_e64 v7, v249, v7, s[4:5]
	v_min_i32_e32 v7, s14, v7
	v_add_u32_e32 v9, 0x7f, v7
	v_ashrrev_i32_e32 v13, 31, v9
	v_lshrrev_b32_e32 v13, 25, v13
	v_add_u32_e32 v9, v9, v13
	v_ashrrev_i32_e32 v9, 7, v9
	v_cndmask_b32_e32 v9, 1, v9, vcc
	v_cmp_lt_i32_e64 s[4:5], 1, v9
	s_nop 1
	v_cndmask_b32_e64 v9, v9, v12, s[4:5]
	v_sub_u32_e32 v13, 0, v9
	v_max_i32_e32 v13, v9, v13
	v_cvt_f32_u32_e32 v14, v13
	v_readlane_b32 s4, v253, 46
	v_add3_u32 v7, v7, v9, -1
	s_nop 0
	v_mov_b32_e32 v12, s4
	v_cmp_lt_i32_e64 s[4:5], 1, v9
	ds_write_b32 v12, v9
	v_xor_b32_e32 v9, v7, v9
	v_cndmask_b32_e64 v12, -1, v10, s[4:5]
	v_cndmask_b32_e64 v10, v10, v11, s[4:5]
	v_rcp_iflag_f32_e32 v11, v14
	ds_write_b32 v15, v12
	v_sub_u32_e32 v12, 0, v7
	v_max_i32_e32 v7, v7, v12
	v_mul_f32_e32 v11, 0x4f7ffffe, v11
	v_cvt_u32_f32_e32 v11, v11
	v_sub_u32_e32 v12, 0, v13
	v_ashrrev_i32_e32 v9, 31, v9
	v_mov_b32_e32 v14, s7
	v_mul_lo_u32 v12, v12, v11
	v_mul_hi_u32 v12, v11, v12
	v_add_u32_e32 v11, v11, v12
	v_mul_hi_u32 v11, v7, v11
	v_mul_lo_u32 v12, v11, v13
	v_sub_u32_e32 v7, v7, v12
	v_add_u32_e32 v12, 1, v11
	v_cmp_ge_u32_e64 s[4:5], v7, v13
	v_readlane_b32 s7, v253, 53
	s_nop 0
	v_cndmask_b32_e64 v11, v11, v12, s[4:5]
	v_sub_u32_e32 v12, v7, v13
	v_cndmask_b32_e64 v7, v7, v12, s[4:5]
	v_add_u32_e32 v12, 1, v11
	v_cmp_ge_u32_e64 s[4:5], v7, v13
	v_mov_b32_e32 v15, s7
	v_readlane_b32 s7, v253, 56
	v_cndmask_b32_e64 v7, v11, v12, s[4:5]
	v_cvt_i32_f32_e32 v11, v8
	v_xor_b32_e32 v7, v7, v9
	v_readlane_b32 s4, v253, 48
	v_sub_u32_e32 v7, v7, v9
	s_nop 0
	v_mov_b32_e32 v9, s4
	ds_write_b32 v9, v7
	v_lshl_add_u32 v7, v11, 1, v248
	v_ashrrev_i32_e32 v9, 31, v7
	v_lshrrev_b32_e32 v9, 26, v9
	v_add_u32_e32 v7, v7, v9
	v_ashrrev_i32_e32 v7, 6, v7
	v_add_u32_e32 v7, 2, v7
	v_cmp_gt_f32_e64 s[4:5], s15, v8
	s_nop 1
	v_cndmask_b32_e64 v7, v249, v7, s[4:5]
	v_min_i32_e32 v7, s14, v7
	v_add_u32_e32 v8, 0x7f, v7
	v_ashrrev_i32_e32 v9, 31, v8
	v_lshrrev_b32_e32 v9, 25, v9
	v_add_u32_e32 v8, v8, v9
	v_ashrrev_i32_e32 v8, 7, v8
	v_add_u32_e32 v9, s13, v10
	v_cndmask_b32_e32 v8, 1, v8, vcc
	v_cmp_lt_u32_e64 s[4:5], s6, v9
	s_nop 1
	v_cndmask_b32_e64 v11, 2, 1, s[4:5]
	v_cmp_lt_i32_e64 s[4:5], 1, v8
	s_nop 1
	v_cndmask_b32_e64 v8, v8, v11, s[4:5]
	v_sub_u32_e32 v12, 0, v8
	v_max_i32_e32 v12, v8, v12
	v_cvt_f32_u32_e32 v13, v12
	v_readlane_b32 s4, v253, 49
	v_add3_u32 v7, v7, v8, -1
	s_nop 0
	v_mov_b32_e32 v11, s4
	v_cmp_lt_i32_e64 s[4:5], 1, v8
	ds_write_b32 v11, v8
	v_xor_b32_e32 v8, v7, v8
	v_cndmask_b32_e64 v11, -1, v10, s[4:5]
	v_cndmask_b32_e64 v10, v10, v9, s[4:5]
	v_rcp_iflag_f32_e32 v9, v13
	ds_write_b32 v14, v11
	v_sub_u32_e32 v11, 0, v7
	v_max_i32_e32 v7, v7, v11
	v_mul_f32_e32 v9, 0x4f7ffffe, v9
	v_cvt_u32_f32_e32 v9, v9
	v_sub_u32_e32 v11, 0, v12
	v_ashrrev_i32_e32 v8, 31, v8
	v_mul_lo_u32 v11, v11, v9
	v_mul_hi_u32 v11, v9, v11
	v_add_u32_e32 v9, v9, v11
	v_mul_hi_u32 v9, v7, v9
	v_mul_lo_u32 v11, v9, v12
	v_sub_u32_e32 v7, v7, v11
	v_add_u32_e32 v11, 1, v9
	v_cmp_ge_u32_e64 s[4:5], v7, v12
	s_nop 1
	v_cndmask_b32_e64 v9, v9, v11, s[4:5]
	v_sub_u32_e32 v11, v7, v12
	v_cndmask_b32_e64 v7, v7, v11, s[4:5]
	v_add_u32_e32 v11, 1, v9
	v_cmp_ge_u32_e64 s[4:5], v7, v12
	s_nop 1
	v_cndmask_b32_e64 v7, v9, v11, s[4:5]
	v_xor_b32_e32 v7, v7, v8
	v_readlane_b32 s4, v253, 51
	v_sub_u32_e32 v7, v7, v8
	v_add_u32_e32 v11, s13, v10
	v_mov_b32_e32 v8, s4
	s_mov_b32 s4, 0x4035676d
	s_mov_b32 s5, 0x405fcbf4
	ds_write_b32 v8, v7
	v_pk_add_f32 v[8:9], v[6:7], s[4:5] op_sel_hi:[0,1]
	s_mov_b32 s4, 0x413504f3
	s_mov_b32 s5, 0x41000000
	v_pk_add_f32 v[8:9], v[8:9], s[16:17] op_sel_hi:[1,0]
	s_mov_b32 s18, s5
	v_pk_mul_f32 v[8:9], v[8:9], s[18:19]
	s_mov_b32 s5, s19
	v_cvt_i32_f32_e32 v7, v9
	v_writelane_b32 v254, s4, 9
	v_lshl_add_u32 v7, v7, 1, v248
	v_ashrrev_i32_e32 v13, 31, v7
	v_lshrrev_b32_e32 v13, 26, v13
	v_add_u32_e32 v7, v7, v13
	v_writelane_b32 v254, s5, 10
	v_cmp_lt_u32_e64 s[4:5], s6, v11
; __device__ __forceinline__ int diff_radius(float bnat, int h) {
;     const float slope_n = exp2f(-(float)(h + 1));
;     const float dn = (2.0f * bnat + logf(2.0f / (1.0f - expf(-slope_n))) + 22.18f) / slope_n;
;     return (dn < 1.0e6f) ? (int)dn + 1 : 1000000;
; }
	v_ashrrev_i32_e32 v7, 6, v7
	v_add_u32_e32 v7, 2, v7
	v_cndmask_b32_e64 v12, 2, 1, s[4:5]
	v_cmp_gt_f32_e64 s[4:5], s15, v9
	s_nop 1
	v_cndmask_b32_e64 v7, v249, v7, s[4:5]
	v_min_i32_e32 v7, s14, v7
	v_add_u32_e32 v9, 0x7f, v7
	v_ashrrev_i32_e32 v13, 31, v9
	v_lshrrev_b32_e32 v13, 25, v13
	v_add_u32_e32 v9, v9, v13
	v_ashrrev_i32_e32 v9, 7, v9
	v_cndmask_b32_e32 v9, 1, v9, vcc
	v_cmp_lt_i32_e64 s[4:5], 1, v9
	s_nop 1
	v_cndmask_b32_e64 v9, v9, v12, s[4:5]
	v_sub_u32_e32 v13, 0, v9
	v_max_i32_e32 v13, v9, v13
	v_cvt_f32_u32_e32 v14, v13
	v_readlane_b32 s4, v253, 52
	v_add3_u32 v7, v7, v9, -1
	s_nop 0
	v_mov_b32_e32 v12, s4
	v_cmp_lt_i32_e64 s[4:5], 1, v9
	ds_write_b32 v12, v9
	v_xor_b32_e32 v9, v7, v9
	v_cndmask_b32_e64 v12, -1, v10, s[4:5]
	v_cndmask_b32_e64 v10, v10, v11, s[4:5]
	v_rcp_iflag_f32_e32 v11, v14
	ds_write_b32 v15, v12
	v_sub_u32_e32 v12, 0, v7
	v_max_i32_e32 v7, v7, v12
	v_mul_f32_e32 v11, 0x4f7ffffe, v11
	v_cvt_u32_f32_e32 v11, v11
	v_sub_u32_e32 v12, 0, v13
	v_ashrrev_i32_e32 v9, 31, v9
	v_mov_b32_e32 v14, s7
	v_mul_lo_u32 v12, v12, v11
	v_mul_hi_u32 v12, v11, v12
	v_add_u32_e32 v11, v11, v12
	v_mul_hi_u32 v11, v7, v11
	v_mul_lo_u32 v12, v11, v13
	v_sub_u32_e32 v7, v7, v12
	v_add_u32_e32 v12, 1, v11
	v_cmp_ge_u32_e64 s[4:5], v7, v13
	v_readlane_b32 s7, v253, 59
	s_nop 0
	v_cndmask_b32_e64 v11, v11, v12, s[4:5]
	v_sub_u32_e32 v12, v7, v13
	v_cndmask_b32_e64 v7, v7, v12, s[4:5]
	v_add_u32_e32 v12, 1, v11
	v_cmp_ge_u32_e64 s[4:5], v7, v13
	s_nop 1
	v_cndmask_b32_e64 v7, v11, v12, s[4:5]
	v_cvt_i32_f32_e32 v11, v8
	v_xor_b32_e32 v7, v7, v9
	v_readlane_b32 s4, v253, 54
	v_sub_u32_e32 v7, v7, v9
	s_nop 0
	v_mov_b32_e32 v9, s4
	ds_write_b32 v9, v7
	v_lshl_add_u32 v7, v11, 1, v248
	v_ashrrev_i32_e32 v9, 31, v7
	v_lshrrev_b32_e32 v9, 26, v9
	v_add_u32_e32 v7, v7, v9
	v_ashrrev_i32_e32 v7, 6, v7
	v_add_u32_e32 v7, 2, v7
	v_cmp_gt_f32_e64 s[4:5], s15, v8
	s_nop 1
	v_cndmask_b32_e64 v7, v249, v7, s[4:5]
	v_min_i32_e32 v7, s14, v7
	v_add_u32_e32 v8, 0x7f, v7
	v_ashrrev_i32_e32 v9, 31, v8
	v_lshrrev_b32_e32 v9, 25, v9
	v_add_u32_e32 v8, v8, v9
	v_ashrrev_i32_e32 v8, 7, v8
	v_add_u32_e32 v9, s13, v10
	v_cndmask_b32_e32 v8, 1, v8, vcc
	v_cmp_lt_u32_e64 s[4:5], s6, v9
	s_nop 1
	v_cndmask_b32_e64 v11, 2, 1, s[4:5]
	v_cmp_lt_i32_e64 s[4:5], 1, v8
	s_nop 1
	v_cndmask_b32_e64 v8, v8, v11, s[4:5]
	v_sub_u32_e32 v12, 0, v8
	v_max_i32_e32 v12, v8, v12
	v_cvt_f32_u32_e32 v13, v12
	v_readlane_b32 s4, v253, 55
	v_add3_u32 v7, v7, v8, -1
	s_nop 0
	v_mov_b32_e32 v11, s4
	v_cmp_lt_i32_e64 s[4:5], 1, v8
	ds_write_b32 v11, v8
	v_xor_b32_e32 v8, v7, v8
	v_cndmask_b32_e64 v11, -1, v10, s[4:5]
	v_cndmask_b32_e64 v9, v10, v9, s[4:5]
	v_rcp_iflag_f32_e32 v10, v13
	ds_write_b32 v14, v11
	v_sub_u32_e32 v11, 0, v7
	v_max_i32_e32 v7, v7, v11
	v_mul_f32_e32 v10, 0x4f7ffffe, v10
	v_cvt_u32_f32_e32 v10, v10
	v_sub_u32_e32 v11, 0, v12
	v_ashrrev_i32_e32 v8, 31, v8
	v_mov_b32_e32 v14, s7
	v_mul_lo_u32 v11, v11, v10
	v_mul_hi_u32 v11, v10, v11
	v_add_u32_e32 v10, v10, v11
	v_mul_hi_u32 v10, v7, v10
	v_mul_lo_u32 v11, v10, v12
	v_sub_u32_e32 v7, v7, v11
	v_add_u32_e32 v11, 1, v10
	v_cmp_ge_u32_e64 s[4:5], v7, v12
	s_nop 1
	v_cndmask_b32_e64 v10, v10, v11, s[4:5]
	v_sub_u32_e32 v11, v7, v12
	v_cndmask_b32_e64 v7, v7, v11, s[4:5]
	v_add_u32_e32 v11, 1, v10
	v_cmp_ge_u32_e64 s[4:5], v7, v12
	s_nop 1
	v_cndmask_b32_e64 v7, v10, v11, s[4:5]
	v_xor_b32_e32 v7, v7, v8
	v_readlane_b32 s4, v253, 57
	v_sub_u32_e32 v7, v7, v8
	v_add_u32_e32 v10, s13, v9
	v_mov_b32_e32 v8, s4
	s_mov_b32 s4, 0x3fd01d78
	s_mov_b32 s5, 0x400ceaed
	ds_write_b32 v8, v7
	v_pk_add_f32 v[6:7], v[6:7], s[4:5] op_sel_hi:[0,1]
	s_mov_b32 s4, 2.0
	v_pk_add_f32 v[6:7], v[6:7], s[16:17] op_sel_hi:[1,0]
	s_mov_b32 s5, 4.0
	v_pk_mul_f32 v[6:7], v[6:7], s[4:5]
; __device__ __forceinline__ int diff_radius(float bnat, int h) {
;     const float slope_n = exp2f(-(float)(h + 1));
;     const float dn = (2.0f * bnat + logf(2.0f / (1.0f - expf(-slope_n))) + 22.18f) / slope_n;
;     return (dn < 1.0e6f) ? (int)dn + 1 : 1000000;
; }
	v_cmp_lt_u32_e64 s[4:5], s6, v10
	v_cvt_i32_f32_e32 v8, v7
	v_lshl_add_u32 v8, v8, 1, v248
	v_ashrrev_i32_e32 v12, 31, v8
	v_lshrrev_b32_e32 v12, 26, v12
	v_add_u32_e32 v8, v8, v12
	v_ashrrev_i32_e32 v8, 6, v8
	v_cndmask_b32_e64 v11, 2, 1, s[4:5]
	v_add_u32_e32 v8, 2, v8
	v_cmp_gt_f32_e64 s[4:5], s15, v7
	s_nop 1
	v_cndmask_b32_e64 v7, v249, v8, s[4:5]
	v_min_i32_e32 v7, s14, v7
	v_add_u32_e32 v8, 0x7f, v7
	v_ashrrev_i32_e32 v12, 31, v8
	v_lshrrev_b32_e32 v12, 25, v12
	v_add_u32_e32 v8, v8, v12
	v_ashrrev_i32_e32 v8, 7, v8
	v_cndmask_b32_e32 v8, 1, v8, vcc
	v_cmp_lt_i32_e64 s[4:5], 1, v8
	s_nop 1
	v_cndmask_b32_e64 v8, v8, v11, s[4:5]
	v_sub_u32_e32 v12, 0, v8
	v_max_i32_e32 v12, v8, v12
	v_cvt_f32_u32_e32 v13, v12
	v_readlane_b32 s4, v253, 58
	v_add3_u32 v7, v7, v8, -1
	s_nop 0
	v_mov_b32_e32 v11, s4
	v_cmp_lt_i32_e64 s[4:5], 1, v8
	ds_write_b32 v11, v8
	v_xor_b32_e32 v8, v7, v8
	v_cndmask_b32_e64 v11, -1, v9, s[4:5]
	v_cndmask_b32_e64 v9, v9, v10, s[4:5]
	v_rcp_iflag_f32_e32 v10, v13
	ds_write_b32 v14, v11
	v_sub_u32_e32 v11, 0, v7
	v_max_i32_e32 v7, v7, v11
	v_mul_f32_e32 v10, 0x4f7ffffe, v10
	v_cvt_u32_f32_e32 v10, v10
	v_sub_u32_e32 v11, 0, v12
	v_ashrrev_i32_e32 v8, 31, v8
	v_mul_lo_u32 v11, v11, v10
	v_mul_hi_u32 v11, v10, v11
	v_add_u32_e32 v10, v10, v11
	v_mul_hi_u32 v10, v7, v10
	v_mul_lo_u32 v11, v10, v12
	v_sub_u32_e32 v7, v7, v11
	v_add_u32_e32 v11, 1, v10
	v_cmp_ge_u32_e64 s[4:5], v7, v12
	s_nop 1
	v_cndmask_b32_e64 v10, v10, v11, s[4:5]
	v_sub_u32_e32 v11, v7, v12
	v_cndmask_b32_e64 v7, v7, v11, s[4:5]
	v_add_u32_e32 v11, 1, v10
	v_cmp_ge_u32_e64 s[4:5], v7, v12
	s_nop 1
	v_cndmask_b32_e64 v7, v10, v11, s[4:5]
	v_cvt_i32_f32_e32 v10, v6
	v_xor_b32_e32 v7, v7, v8
	v_readlane_b32 s4, v253, 60
	v_sub_u32_e32 v7, v7, v8
	s_nop 0
	v_mov_b32_e32 v8, s4
	ds_write_b32 v8, v7
	v_lshl_add_u32 v7, v10, 1, v248
	v_ashrrev_i32_e32 v8, 31, v7
	v_lshrrev_b32_e32 v8, 26, v8
	v_add_u32_e32 v7, v7, v8
	v_ashrrev_i32_e32 v7, 6, v7
	v_add_u32_e32 v7, 2, v7
	v_cmp_gt_f32_e64 s[4:5], s15, v6
	s_nop 1
	v_cndmask_b32_e64 v6, v249, v7, s[4:5]
	v_min_i32_e32 v6, s14, v6
	v_add_u32_e32 v7, 0x7f, v6
	v_ashrrev_i32_e32 v8, 31, v7
	v_lshrrev_b32_e32 v8, 25, v8
	v_add_u32_e32 v7, v7, v8
	v_ashrrev_i32_e32 v7, 7, v7
	v_add_u32_e32 v8, s13, v9
	v_cndmask_b32_e32 v7, 1, v7, vcc
	v_cmp_lt_u32_e32 vcc, s6, v8
	v_readlane_b32 s4, v253, 61
	s_mov_b32 s5, -1
	v_cndmask_b32_e64 v8, 2, 1, vcc
	v_cmp_lt_i32_e32 vcc, 1, v7
	s_nop 1
	v_cndmask_b32_e32 v7, v7, v8, vcc
	v_mov_b32_e32 v8, s4
	ds_write_b32 v8, v7
	v_sub_u32_e32 v8, 0, v7
	v_max_i32_e32 v8, v7, v8
	v_cvt_f32_u32_e32 v10, v8
	v_cmp_lt_i32_e32 vcc, 1, v7
	v_readlane_b32 s4, v253, 62
	v_add3_u32 v6, v6, v7, -1
	v_cndmask_b32_e32 v9, -1, v9, vcc
	v_mov_b32_e32 v11, s4
	ds_write_b32 v11, v9
	v_rcp_iflag_f32_e32 v9, v10
	v_sub_u32_e32 v10, 0, v6
	v_xor_b32_e32 v7, v6, v7
	v_max_i32_e32 v6, v6, v10
	v_mul_f32_e32 v9, 0x4f7ffffe, v9
	v_cvt_u32_f32_e32 v9, v9
	v_sub_u32_e32 v10, 0, v8
	v_ashrrev_i32_e32 v7, 31, v7
	v_readlane_b32 s4, v253, 63
	v_mul_lo_u32 v10, v10, v9
	v_mul_hi_u32 v10, v9, v10
	v_add_u32_e32 v9, v9, v10
	v_mul_hi_u32 v9, v6, v9
	v_mul_lo_u32 v10, v9, v8
	v_sub_u32_e32 v6, v6, v10
	v_add_u32_e32 v10, 1, v9
	v_cmp_ge_u32_e32 vcc, v6, v8
	s_nop 1
	v_cndmask_b32_e32 v9, v9, v10, vcc
	v_sub_u32_e32 v10, v6, v8
	v_cndmask_b32_e32 v6, v6, v10, vcc
	v_add_u32_e32 v10, 1, v9
	v_cmp_ge_u32_e32 vcc, v6, v8
	s_nop 1
	v_cndmask_b32_e32 v6, v9, v10, vcc
	v_xor_b32_e32 v6, v6, v7
	v_sub_u32_e32 v6, v6, v7
	v_mov_b32_e32 v7, s4
	ds_write_b32 v7, v6
	ds_read_b32 v5, v5
	s_waitcnt lgkmcnt(0)
	v_cmp_lt_i32_e32 vcc, -1, v5
	s_cbranch_vccz .LBB0_1055
	v_mov_b32_e32 v5, s72
	ds_read_b32 v5, v5
	s_mov_b32 s5, 7
	s_branch .LBB0_1056
